# v036: v032 + pre-norm GEMM tile epilogues: the 8 row sum-of-squares loads issued first thing after the K loop (before alignment barrier, dispatch, descriptor read and address math)
# speedup vs baseline: 1.0029x; 1.0029x over previous
.LBB0_1053:
	s_cmp_lt_i32 s28, 8
	s_cbranch_scc0 .Lpn_skip
	s_cmp_eq_u32 s28, 5
	s_cbranch_scc1 .Lpn_skip
	v_add_u32_e32 v184, s63, v194
	v_ashrrev_i32_e32 v185, 31, v184
	v_lshlrev_b64 v[184:185], 6, v[184:185]
	v_lshl_add_u64 v[184:185], v[210:211], 0, v[184:185]
	global_load_dwordx4 v[128:131], v[184:185], off
	global_load_dwordx4 v[132:135], v[184:185], off offset:1024
	global_load_dwordx4 v[136:139], v[184:185], off offset:2048
	global_load_dwordx4 v[140:143], v[184:185], off offset:3072
	v_add_co_u32_e32 v184, vcc, 0x2000, v184
	s_nop 1
	v_addc_co_u32_e32 v185, vcc, 0, v185, vcc
	global_load_dwordx4 v[164:167], v[184:185], off
	global_load_dwordx4 v[168:171], v[184:185], off offset:1024
	global_load_dwordx4 v[176:179], v[184:185], off offset:2048
	global_load_dwordx4 v[180:183], v[184:185], off offset:3072

.LBB0_1062:
	v_readlane_b32 s0, v250, 54
	v_add_u32_e32 v162, 16, v144
	v_add_u32_e32 v158, 32, v144
	v_add_u32_e32 v154, 48, v144
	v_add_u32_e32 v146, 0x80, v144
	v_add_u32_e32 v150, 0x90, v144
	v_mov_b32_e32 v184, s0
	v_ashrrev_i32_e32 v163, 31, v162
	v_ashrrev_i32_e32 v159, 31, v158
	v_ashrrev_i32_e32 v155, 31, v154
	v_ashrrev_i32_e32 v147, 31, v146
	v_ashrrev_i32_e32 v151, 31, v150
	ds_read_b32 v156, v184
	s_waitcnt lgkmcnt(0)
	v_lshlrev_b64 v[146:147], 6, v[146:147]
	v_lshlrev_b64 v[148:149], 6, v[150:151]
	v_lshl_add_u64 v[146:147], v[210:211], 0, v[146:147]
	v_lshl_add_u64 v[148:149], v[210:211], 0, v[148:149]
	s_nop 0
	s_nop 0
	s_nop 0
	s_nop 0
	v_add_u32_e32 v148, 0xa0, v144
	v_ashrrev_i32_e32 v149, 31, v148
	v_lshlrev_b64 v[146:147], 6, v[148:149]
	v_lshl_add_u64 v[146:147], v[210:211], 0, v[146:147]
	v_add_u32_e32 v146, 0xb0, v144
	v_ashrrev_i32_e32 v147, 31, v146
	v_lshlrev_b64 v[152:153], 6, v[146:147]
	v_lshl_add_u64 v[152:153], v[210:211], 0, v[152:153]
	v_cmp_lt_i32_e32 vcc, v223, v218
	v_readfirstlane_b32 s0, v156
	s_mov_b64 s[20:21], -1
	v_cndmask_b32_e32 v147, v217, v223, vcc
	v_lshlrev_b32_e32 v147, 2, v147
	v_cmp_lt_i32_e32 vcc, v224, v218
	s_mov_b64 s[30:31], 0
	s_cmp_lt_i32 s28, 2
	v_cndmask_b32_e32 v149, v217, v224, vcc
	v_lshlrev_b32_e32 v149, 2, v149
	s_waitcnt vmcnt(0) lgkmcnt(0)
	v_add_f32_e32 v128, v128, v129
	v_add_f32_e32 v129, v130, v131
	v_add_f32_e32 v130, v132, v133
	v_add_f32_e32 v131, v134, v135
	v_add_f32_e32 v132, v136, v137
	v_add_f32_e32 v133, v138, v139
	v_add_f32_e32 v134, v140, v141
	v_add_f32_e32 v135, v142, v143
	v_add_f32_e32 v136, v164, v165
	v_add_f32_e32 v137, v166, v167
	v_add_f32_e32 v138, v168, v169
	v_add_f32_e32 v139, v170, v171
	v_add_f32_e32 v140, v176, v177
	v_add_f32_e32 v141, v178, v179
	v_add_f32_e32 v142, v180, v181
	v_add_f32_e32 v143, v182, v183
	v_add_f32_e32 v128, v128, v129
	v_add_f32_e32 v130, v130, v131
	v_add_f32_e32 v131, v132, v133
	v_add_f32_e32 v132, v134, v135
	v_add_f32_e32 v133, v136, v137
	v_add_f32_e32 v134, v138, v139
	v_add_f32_e32 v136, v140, v141
	v_add_f32_e32 v139, v142, v143
	ds_bpermute_b32 v129, v147, v128
	ds_bpermute_b32 v135, v147, v130
	ds_bpermute_b32 v137, v147, v131
	ds_bpermute_b32 v142, v147, v132
	ds_bpermute_b32 v143, v147, v133
	ds_bpermute_b32 v151, v147, v134
	ds_bpermute_b32 v152, v147, v136
	ds_bpermute_b32 v147, v147, v139
	s_waitcnt lgkmcnt(7)
	v_add_f32_e32 v140, v128, v129
	s_waitcnt lgkmcnt(6)
	v_add_f32_e32 v138, v130, v135
	s_waitcnt lgkmcnt(5)
	v_add_f32_e32 v137, v131, v137
	s_waitcnt lgkmcnt(4)
	v_add_f32_e32 v135, v132, v142
	s_waitcnt lgkmcnt(3)
	v_add_f32_e32 v132, v133, v143
	s_waitcnt lgkmcnt(2)
	v_add_f32_e32 v130, v134, v151
	s_waitcnt lgkmcnt(1)
	v_add_f32_e32 v129, v136, v152
	s_waitcnt lgkmcnt(0)
	v_add_f32_e32 v128, v139, v147
	ds_bpermute_b32 v141, v149, v140
	ds_bpermute_b32 v143, v149, v138
	ds_bpermute_b32 v142, v149, v137
	ds_bpermute_b32 v139, v149, v135
	ds_bpermute_b32 v136, v149, v132
	ds_bpermute_b32 v134, v149, v130
	ds_bpermute_b32 v133, v149, v129
	ds_bpermute_b32 v131, v149, v128
	s_waitcnt lgkmcnt(7)
	v_add_f32_e32 v140, v140, v141
	s_waitcnt lgkmcnt(6)
	v_add_f32_e32 v138, v138, v143
	s_waitcnt lgkmcnt(5)
	v_add_f32_e32 v137, v137, v142
	s_waitcnt lgkmcnt(4)
	v_add_f32_e32 v135, v135, v139
	s_waitcnt lgkmcnt(3)
	v_add_f32_e32 v132, v132, v136
	s_waitcnt lgkmcnt(2)
	v_add_f32_e32 v130, v130, v134
	s_waitcnt lgkmcnt(1)
	v_add_f32_e32 v129, v129, v133
	s_waitcnt lgkmcnt(0)
	v_add_f32_e32 v128, v128, v131
	v_fmamk_f32 v140, v140, 0x3a800000, v215
	v_fmamk_f32 v138, v138, 0x3a800000, v215
	v_fmamk_f32 v137, v137, 0x3a800000, v215
	v_fmamk_f32 v135, v135, 0x3a800000, v215
	v_fmamk_f32 v132, v132, 0x3a800000, v215
	v_fmamk_f32 v130, v130, 0x3a800000, v215
	v_fmamk_f32 v129, v129, 0x3a800000, v215
	v_fmamk_f32 v128, v128, 0x3a800000, v215
	v_rsq_f32_e32 v140, v140
	v_rsq_f32_e32 v138, v138
	v_rsq_f32_e32 v137, v137
	v_rsq_f32_e32 v135, v135
	v_rsq_f32_e32 v132, v132
	v_rsq_f32_e32 v130, v130
	v_rsq_f32_e32 v129, v129
	v_rsq_f32_e32 v128, v128
	v_mul_f32_e32 v176, s0, v140
	v_mul_f32_e32 v170, s0, v138
	v_mul_f32_e32 v168, s0, v137
	v_mul_f32_e32 v166, s0, v135
	v_mul_f32_e32 v164, s0, v132
	v_mul_f32_e32 v160, s0, v130
	v_mul_f32_e32 v156, s0, v129
	v_mul_f32_e32 v152, s0, v128
	s_mov_b64 s[0:1], 0
	s_cbranch_scc1 .LBB0_1075
	s_cmp_gt_i32 s28, 2
	s_cbranch_scc0 .LBB0_1072
	s_cmp_gt_i32 s28, 6
	s_cbranch_scc0 .LBB0_1068
	s_cmp_eq_u32 s28, 7
	s_mov_b64 s[0:1], -1
	s_cbranch_scc0 .LBB0_1067
	v_readlane_b32 s0, v251, 4
	s_ashr_i32 s67, s66, 31
	v_ashrrev_i32_e32 v175, 31, v174
	v_mov_b32_e32 v128, s0
	ds_read_b32 v128, v128
	v_readlane_b32 s0, v251, 5
	s_lshl_b64 s[20:21], s[66:67], 1
	v_mul_f32_e32 v132, v126, v176
	s_waitcnt lgkmcnt(0)
	v_mov_b32_e32 v128, s0
	ds_read_b32 v128, v128
	v_readlane_b32 s0, v251, 6
	v_mul_f32_e32 v133, v127, v176
	v_mul_f32_e32 v136, v120, v176
	s_waitcnt lgkmcnt(0)
	v_mov_b32_e32 v128, s0
	v_readlane_b32 s0, v251, 7
	ds_read_b32 v128, v128
	v_mul_f32_e32 v137, v121, v176
	v_mov_b32_e32 v129, s0
	v_readlane_b32 s0, v250, 53
	ds_read_b32 v129, v129
	v_mul_f32_e32 v138, v122, v176
	v_mov_b32_e32 v130, s0
	ds_read_b32 v130, v130
	s_waitcnt lgkmcnt(2)
	v_readfirstlane_b32 s0, v128
	s_waitcnt lgkmcnt(1)
	v_readfirstlane_b32 s1, v129
	v_mul_f32_e32 v139, v123, v176
	v_max_f32_e32 v132, 0, v132
	s_waitcnt lgkmcnt(0)
	v_readfirstlane_b32 s5, v130
	v_max_f32_e32 v133, 0, v133
	v_max_f32_e32 v136, 0, v136
	v_mad_i64_i32 v[128:129], s[16:17], s5, v144, 0
	v_lshl_add_u64 v[128:129], v[128:129], 1, s[0:1]
	v_lshl_add_u64 v[130:131], v[128:129], 0, s[20:21]
	v_lshlrev_b64 v[128:129], 1, v[174:175]
	v_lshl_add_u64 v[134:135], v[130:131], 0, v[128:129]
	v_mul_f32_e32 v130, v124, v176
	v_mul_f32_e32 v131, v125, v176
	v_max_f32_e32 v130, 0, v130
	v_max_f32_e32 v131, 0, v131
	v_max_f32_e32 v137, 0, v137
	v_max_f32_e32 v138, 0, v138
	v_max_f32_e32 v139, 0, v139
	v_pk_mul_f32 v[130:131], v[130:131], v[130:131]
	v_pk_mul_f32 v[132:133], v[132:133], v[132:133]
	v_pk_mul_f32 v[136:137], v[136:137], v[136:137]
	v_pk_mul_f32 v[138:139], v[138:139], v[138:139]
	v_cvt_pk_bf16_f32 v130, v130, v131
	v_cvt_pk_bf16_f32 v131, v132, v133
	v_cvt_pk_bf16_f32 v132, v136, v137
	v_cvt_pk_bf16_f32 v133, v138, v139
	global_store_dwordx4 v[134:135], v[130:133], off
	v_mul_f32_e32 v136, v88, v176
	v_mul_f32_e32 v137, v89, v176
	v_mul_f32_e32 v130, v92, v176
	v_mul_f32_e32 v131, v93, v176
	v_mul_f32_e32 v132, v94, v176
	v_mul_f32_e32 v133, v95, v176
	v_mul_f32_e32 v138, v90, v176
	v_mul_f32_e32 v139, v91, v176
	v_max_f32_e32 v130, 0, v130
	v_max_f32_e32 v131, 0, v131
	v_max_f32_e32 v132, 0, v132
	v_max_f32_e32 v133, 0, v133
	v_max_f32_e32 v136, 0, v136
	v_max_f32_e32 v137, 0, v137
	v_max_f32_e32 v138, 0, v138
	v_max_f32_e32 v139, 0, v139
	v_pk_mul_f32 v[130:131], v[130:131], v[130:131]
	v_pk_mul_f32 v[132:133], v[132:133], v[132:133]
	v_pk_mul_f32 v[136:137], v[136:137], v[136:137]
	v_pk_mul_f32 v[138:139], v[138:139], v[138:139]
	v_cvt_pk_bf16_f32 v130, v130, v131
	v_cvt_pk_bf16_f32 v131, v132, v133
	v_cvt_pk_bf16_f32 v132, v136, v137
	v_cvt_pk_bf16_f32 v133, v138, v139
	global_store_dwordx4 v[134:135], v[130:133], off offset:256
	v_mul_f32_e32 v136, v112, v170
	v_mul_f32_e32 v137, v113, v170
	v_mad_i64_i32 v[130:131], s[16:17], s5, v162, 0
	v_lshl_add_u64 v[130:131], v[130:131], 1, s[0:1]
	v_lshl_add_u64 v[130:131], v[130:131], 0, s[20:21]
	v_lshl_add_u64 v[134:135], v[130:131], 0, v[128:129]
	v_mul_f32_e32 v130, v116, v170
	v_mul_f32_e32 v131, v117, v170
	v_mul_f32_e32 v132, v118, v170
	v_mul_f32_e32 v133, v119, v170
	v_mul_f32_e32 v138, v114, v170
	v_mul_f32_e32 v139, v115, v170
	v_max_f32_e32 v130, 0, v130
	v_max_f32_e32 v131, 0, v131
	v_max_f32_e32 v132, 0, v132
	v_max_f32_e32 v133, 0, v133
	v_max_f32_e32 v136, 0, v136
	v_max_f32_e32 v137, 0, v137
	v_max_f32_e32 v138, 0, v138
	v_max_f32_e32 v139, 0, v139
	v_pk_mul_f32 v[130:131], v[130:131], v[130:131]
	v_pk_mul_f32 v[132:133], v[132:133], v[132:133]
	v_pk_mul_f32 v[136:137], v[136:137], v[136:137]
	v_pk_mul_f32 v[138:139], v[138:139], v[138:139]
	v_cvt_pk_bf16_f32 v130, v130, v131
	v_cvt_pk_bf16_f32 v131, v132, v133
	v_cvt_pk_bf16_f32 v132, v136, v137
	v_cvt_pk_bf16_f32 v133, v138, v139
	global_store_dwordx4 v[134:135], v[130:133], off
	v_mul_f32_e32 v136, v80, v170
	v_mul_f32_e32 v137, v81, v170
	v_mul_f32_e32 v130, v84, v170
	v_mul_f32_e32 v131, v85, v170
	v_mul_f32_e32 v132, v86, v170
	v_mul_f32_e32 v133, v87, v170
	v_mul_f32_e32 v138, v82, v170
	v_mul_f32_e32 v139, v83, v170
	v_max_f32_e32 v130, 0, v130
	v_max_f32_e32 v131, 0, v131
	v_max_f32_e32 v132, 0, v132
	v_max_f32_e32 v133, 0, v133
	v_max_f32_e32 v136, 0, v136
	v_max_f32_e32 v137, 0, v137
	v_max_f32_e32 v138, 0, v138
	v_max_f32_e32 v139, 0, v139
	v_pk_mul_f32 v[130:131], v[130:131], v[130:131]
	v_pk_mul_f32 v[132:133], v[132:133], v[132:133]
	v_pk_mul_f32 v[136:137], v[136:137], v[136:137]
	v_pk_mul_f32 v[138:139], v[138:139], v[138:139]
	v_cvt_pk_bf16_f32 v130, v130, v131
	v_cvt_pk_bf16_f32 v131, v132, v133
	v_cvt_pk_bf16_f32 v132, v136, v137
	v_cvt_pk_bf16_f32 v133, v138, v139
	global_store_dwordx4 v[134:135], v[130:133], off offset:256
	v_mul_f32_e32 v136, v104, v168
	v_mul_f32_e32 v137, v105, v168
	v_mad_i64_i32 v[130:131], s[16:17], s5, v158, 0
	v_lshl_add_u64 v[130:131], v[130:131], 1, s[0:1]
	v_lshl_add_u64 v[130:131], v[130:131], 0, s[20:21]
	v_lshl_add_u64 v[134:135], v[130:131], 0, v[128:129]
	v_mul_f32_e32 v130, v108, v168
	v_mul_f32_e32 v131, v109, v168
	v_mul_f32_e32 v132, v110, v168
	v_mul_f32_e32 v133, v111, v168
	v_mul_f32_e32 v138, v106, v168
	v_mul_f32_e32 v139, v107, v168
	v_max_f32_e32 v130, 0, v130
	v_max_f32_e32 v131, 0, v131
	v_max_f32_e32 v132, 0, v132
	v_max_f32_e32 v133, 0, v133
	v_max_f32_e32 v136, 0, v136
	v_max_f32_e32 v137, 0, v137
	v_max_f32_e32 v138, 0, v138
	v_max_f32_e32 v139, 0, v139
	v_pk_mul_f32 v[130:131], v[130:131], v[130:131]
	v_pk_mul_f32 v[132:133], v[132:133], v[132:133]
	v_pk_mul_f32 v[136:137], v[136:137], v[136:137]
	v_pk_mul_f32 v[138:139], v[138:139], v[138:139]
	v_cvt_pk_bf16_f32 v130, v130, v131
	v_cvt_pk_bf16_f32 v131, v132, v133
	v_cvt_pk_bf16_f32 v132, v136, v137
	v_cvt_pk_bf16_f32 v133, v138, v139
	global_store_dwordx4 v[134:135], v[130:133], off
	v_mul_f32_e32 v136, v72, v168
	v_mul_f32_e32 v137, v73, v168
	v_mul_f32_e32 v130, v76, v168
	v_mul_f32_e32 v131, v77, v168
	v_mul_f32_e32 v132, v78, v168
	v_mul_f32_e32 v133, v79, v168
	v_mul_f32_e32 v138, v74, v168
	v_mul_f32_e32 v139, v75, v168
	v_max_f32_e32 v130, 0, v130
	v_max_f32_e32 v131, 0, v131
	v_max_f32_e32 v132, 0, v132
	v_max_f32_e32 v133, 0, v133
	v_max_f32_e32 v136, 0, v136
	v_max_f32_e32 v137, 0, v137
	v_max_f32_e32 v138, 0, v138
	v_max_f32_e32 v139, 0, v139
	v_pk_mul_f32 v[130:131], v[130:131], v[130:131]
	v_pk_mul_f32 v[132:133], v[132:133], v[132:133]
	v_pk_mul_f32 v[136:137], v[136:137], v[136:137]
	v_pk_mul_f32 v[138:139], v[138:139], v[138:139]
	v_cvt_pk_bf16_f32 v130, v130, v131
	v_cvt_pk_bf16_f32 v131, v132, v133
	v_cvt_pk_bf16_f32 v132, v136, v137
	v_cvt_pk_bf16_f32 v133, v138, v139
	global_store_dwordx4 v[134:135], v[130:133], off offset:256
	v_mul_f32_e32 v136, v96, v166
	v_mul_f32_e32 v137, v97, v166
	v_mad_i64_i32 v[130:131], s[16:17], s5, v154, 0
	v_lshl_add_u64 v[130:131], v[130:131], 1, s[0:1]
	v_lshl_add_u64 v[130:131], v[130:131], 0, s[20:21]
	v_lshl_add_u64 v[134:135], v[130:131], 0, v[128:129]
	v_mul_f32_e32 v130, v100, v166
	v_mul_f32_e32 v131, v101, v166
	v_mul_f32_e32 v132, v102, v166
	v_mul_f32_e32 v133, v103, v166
	v_mul_f32_e32 v138, v98, v166
	v_mul_f32_e32 v139, v99, v166
	v_max_f32_e32 v130, 0, v130
	v_max_f32_e32 v131, 0, v131
	v_max_f32_e32 v132, 0, v132
	v_max_f32_e32 v133, 0, v133
	v_max_f32_e32 v136, 0, v136
	v_max_f32_e32 v137, 0, v137
	v_max_f32_e32 v138, 0, v138
	v_max_f32_e32 v139, 0, v139
	v_pk_mul_f32 v[130:131], v[130:131], v[130:131]
	v_pk_mul_f32 v[132:133], v[132:133], v[132:133]
	v_pk_mul_f32 v[136:137], v[136:137], v[136:137]
	v_pk_mul_f32 v[138:139], v[138:139], v[138:139]
	v_cvt_pk_bf16_f32 v130, v130, v131
	v_cvt_pk_bf16_f32 v131, v132, v133
	v_cvt_pk_bf16_f32 v132, v136, v137
	v_cvt_pk_bf16_f32 v133, v138, v139
	global_store_dwordx4 v[134:135], v[130:133], off
	v_mul_f32_e32 v136, v64, v166
	v_mul_f32_e32 v137, v65, v166
	v_mul_f32_e32 v130, v68, v166
	v_mul_f32_e32 v131, v69, v166
	v_mul_f32_e32 v132, v70, v166
	v_mul_f32_e32 v133, v71, v166
	v_mul_f32_e32 v138, v66, v166
	v_mul_f32_e32 v139, v67, v166
	v_max_f32_e32 v130, 0, v130
	v_max_f32_e32 v131, 0, v131
	v_max_f32_e32 v132, 0, v132
	v_max_f32_e32 v133, 0, v133
	v_max_f32_e32 v136, 0, v136
	v_max_f32_e32 v137, 0, v137
	v_max_f32_e32 v138, 0, v138
	v_max_f32_e32 v139, 0, v139
	v_pk_mul_f32 v[130:131], v[130:131], v[130:131]
	v_pk_mul_f32 v[132:133], v[132:133], v[132:133]
	v_pk_mul_f32 v[136:137], v[136:137], v[136:137]
	v_pk_mul_f32 v[138:139], v[138:139], v[138:139]
	v_cvt_pk_bf16_f32 v130, v130, v131
	v_cvt_pk_bf16_f32 v131, v132, v133
	v_cvt_pk_bf16_f32 v132, v136, v137
	v_cvt_pk_bf16_f32 v133, v138, v139
	global_store_dwordx4 v[134:135], v[130:133], off offset:256
	v_mul_f32_e32 v136, v56, v164
	v_mul_f32_e32 v137, v57, v164
	v_add_u32_e32 v130, s77, v172
	v_mad_i64_i32 v[130:131], s[16:17], s5, v130, 0
	v_lshl_add_u64 v[130:131], v[130:131], 1, s[0:1]
	v_lshl_add_u64 v[130:131], v[130:131], 0, s[20:21]
	v_lshl_add_u64 v[134:135], v[130:131], 0, v[128:129]
	v_mul_f32_e32 v130, v60, v164
	v_mul_f32_e32 v131, v61, v164
	v_mul_f32_e32 v132, v62, v164
	v_mul_f32_e32 v133, v63, v164
	v_mul_f32_e32 v138, v58, v164
	v_mul_f32_e32 v139, v59, v164
	v_max_f32_e32 v130, 0, v130
	v_max_f32_e32 v131, 0, v131
	v_max_f32_e32 v132, 0, v132
	v_max_f32_e32 v133, 0, v133
	v_max_f32_e32 v136, 0, v136
	v_max_f32_e32 v137, 0, v137
	v_max_f32_e32 v138, 0, v138
	v_max_f32_e32 v139, 0, v139
	v_pk_mul_f32 v[130:131], v[130:131], v[130:131]
	v_pk_mul_f32 v[132:133], v[132:133], v[132:133]
	v_pk_mul_f32 v[136:137], v[136:137], v[136:137]
	v_pk_mul_f32 v[138:139], v[138:139], v[138:139]
	v_cvt_pk_bf16_f32 v130, v130, v131
	v_cvt_pk_bf16_f32 v131, v132, v133
	v_cvt_pk_bf16_f32 v132, v136, v137
	v_cvt_pk_bf16_f32 v133, v138, v139
	global_store_dwordx4 v[134:135], v[130:133], off
	v_mul_f32_e32 v136, v24, v164
	v_mul_f32_e32 v137, v25, v164
	v_mul_f32_e32 v130, v28, v164
	v_mul_f32_e32 v131, v29, v164
	v_mul_f32_e32 v132, v30, v164
	v_mul_f32_e32 v133, v31, v164
	v_mul_f32_e32 v138, v26, v164
	v_mul_f32_e32 v139, v27, v164
	v_max_f32_e32 v130, 0, v130
	v_max_f32_e32 v131, 0, v131
	v_max_f32_e32 v132, 0, v132
	v_max_f32_e32 v133, 0, v133
	v_max_f32_e32 v136, 0, v136
	v_max_f32_e32 v137, 0, v137
	v_max_f32_e32 v138, 0, v138
	v_max_f32_e32 v139, 0, v139
	v_pk_mul_f32 v[130:131], v[130:131], v[130:131]
	v_pk_mul_f32 v[132:133], v[132:133], v[132:133]
	v_pk_mul_f32 v[136:137], v[136:137], v[136:137]
	v_pk_mul_f32 v[138:139], v[138:139], v[138:139]
	v_cvt_pk_bf16_f32 v130, v130, v131
	v_cvt_pk_bf16_f32 v131, v132, v133
	v_cvt_pk_bf16_f32 v132, v136, v137
	v_cvt_pk_bf16_f32 v133, v138, v139
	global_store_dwordx4 v[134:135], v[130:133], off offset:256
	v_mul_f32_e32 v136, v48, v160
	v_mul_f32_e32 v137, v49, v160
	v_mad_i64_i32 v[130:131], s[16:17], s5, v150, 0
	v_lshl_add_u64 v[130:131], v[130:131], 1, s[0:1]
	v_lshl_add_u64 v[130:131], v[130:131], 0, s[20:21]
	v_lshl_add_u64 v[134:135], v[130:131], 0, v[128:129]
	v_mul_f32_e32 v130, v52, v160
	v_mul_f32_e32 v131, v53, v160
	v_mul_f32_e32 v132, v54, v160
	v_mul_f32_e32 v133, v55, v160
	v_mul_f32_e32 v138, v50, v160
	v_mul_f32_e32 v139, v51, v160
	v_max_f32_e32 v130, 0, v130
	v_max_f32_e32 v131, 0, v131
	v_max_f32_e32 v132, 0, v132
	v_max_f32_e32 v133, 0, v133
	v_max_f32_e32 v136, 0, v136
	v_max_f32_e32 v137, 0, v137
	v_max_f32_e32 v138, 0, v138
	v_max_f32_e32 v139, 0, v139
	v_pk_mul_f32 v[130:131], v[130:131], v[130:131]
	v_pk_mul_f32 v[132:133], v[132:133], v[132:133]
	v_pk_mul_f32 v[136:137], v[136:137], v[136:137]
	v_pk_mul_f32 v[138:139], v[138:139], v[138:139]
	v_cvt_pk_bf16_f32 v130, v130, v131
	v_cvt_pk_bf16_f32 v131, v132, v133
	v_cvt_pk_bf16_f32 v132, v136, v137
	v_cvt_pk_bf16_f32 v133, v138, v139
	global_store_dwordx4 v[134:135], v[130:133], off
	v_mul_f32_e32 v136, v16, v160
	v_mul_f32_e32 v137, v17, v160
	v_mul_f32_e32 v130, v20, v160
	v_mul_f32_e32 v131, v21, v160
	v_mul_f32_e32 v132, v22, v160
	v_mul_f32_e32 v133, v23, v160
	v_mul_f32_e32 v138, v18, v160
	v_mul_f32_e32 v139, v19, v160
	v_max_f32_e32 v130, 0, v130
	v_max_f32_e32 v131, 0, v131
	v_max_f32_e32 v132, 0, v132
	v_max_f32_e32 v133, 0, v133
	v_max_f32_e32 v136, 0, v136
	v_max_f32_e32 v137, 0, v137
	v_max_f32_e32 v138, 0, v138
	v_max_f32_e32 v139, 0, v139
	v_pk_mul_f32 v[130:131], v[130:131], v[130:131]
	v_pk_mul_f32 v[132:133], v[132:133], v[132:133]
	v_pk_mul_f32 v[136:137], v[136:137], v[136:137]
	v_pk_mul_f32 v[138:139], v[138:139], v[138:139]
	v_cvt_pk_bf16_f32 v130, v130, v131
	v_cvt_pk_bf16_f32 v131, v132, v133
	v_cvt_pk_bf16_f32 v132, v136, v137
	v_cvt_pk_bf16_f32 v133, v138, v139
	global_store_dwordx4 v[134:135], v[130:133], off offset:256
	v_mul_f32_e32 v136, v40, v156
	v_mul_f32_e32 v137, v41, v156
	v_mad_i64_i32 v[130:131], s[16:17], s5, v148, 0
	v_lshl_add_u64 v[130:131], v[130:131], 1, s[0:1]
	v_lshl_add_u64 v[130:131], v[130:131], 0, s[20:21]
	v_lshl_add_u64 v[134:135], v[130:131], 0, v[128:129]
	v_mul_f32_e32 v130, v44, v156
	v_mul_f32_e32 v131, v45, v156
	v_mul_f32_e32 v132, v46, v156
	v_mul_f32_e32 v133, v47, v156
	v_mul_f32_e32 v138, v42, v156
	v_mul_f32_e32 v139, v43, v156
	v_max_f32_e32 v130, 0, v130
	v_max_f32_e32 v131, 0, v131
	v_max_f32_e32 v132, 0, v132
	v_max_f32_e32 v133, 0, v133
	v_max_f32_e32 v136, 0, v136
	v_max_f32_e32 v137, 0, v137
	v_max_f32_e32 v138, 0, v138
	v_max_f32_e32 v139, 0, v139
	v_pk_mul_f32 v[130:131], v[130:131], v[130:131]
	v_pk_mul_f32 v[132:133], v[132:133], v[132:133]
	v_pk_mul_f32 v[136:137], v[136:137], v[136:137]
	v_pk_mul_f32 v[138:139], v[138:139], v[138:139]
	v_cvt_pk_bf16_f32 v130, v130, v131
	v_cvt_pk_bf16_f32 v131, v132, v133
	v_cvt_pk_bf16_f32 v132, v136, v137
	v_cvt_pk_bf16_f32 v133, v138, v139
	global_store_dwordx4 v[134:135], v[130:133], off
	v_mul_f32_e32 v136, v8, v156
	v_mul_f32_e32 v137, v9, v156
	v_mul_f32_e32 v130, v12, v156
	v_mul_f32_e32 v131, v13, v156
	v_mul_f32_e32 v132, v14, v156
	v_mul_f32_e32 v133, v15, v156
	v_mul_f32_e32 v138, v10, v156
	v_mul_f32_e32 v139, v11, v156
	v_max_f32_e32 v130, 0, v130
	v_max_f32_e32 v131, 0, v131
	v_max_f32_e32 v132, 0, v132
	v_max_f32_e32 v133, 0, v133
	v_max_f32_e32 v136, 0, v136
	v_max_f32_e32 v137, 0, v137
	v_max_f32_e32 v138, 0, v138
	v_max_f32_e32 v139, 0, v139
	v_pk_mul_f32 v[130:131], v[130:131], v[130:131]
	v_pk_mul_f32 v[132:133], v[132:133], v[132:133]
	v_pk_mul_f32 v[136:137], v[136:137], v[136:137]
	v_pk_mul_f32 v[138:139], v[138:139], v[138:139]
	v_cvt_pk_bf16_f32 v130, v130, v131
	v_cvt_pk_bf16_f32 v131, v132, v133
	v_cvt_pk_bf16_f32 v132, v136, v137
	v_cvt_pk_bf16_f32 v133, v138, v139
	global_store_dwordx4 v[134:135], v[130:133], off offset:256
	v_mul_f32_e32 v134, v32, v152
	v_mul_f32_e32 v135, v33, v152
	v_mad_i64_i32 v[130:131], s[16:17], s5, v146, 0
	v_lshl_add_u64 v[130:131], v[130:131], 1, s[0:1]
	v_lshl_add_u64 v[130:131], v[130:131], 0, s[20:21]
	v_lshl_add_u64 v[132:133], v[130:131], 0, v[128:129]
	v_mul_f32_e32 v128, v36, v152
	v_mul_f32_e32 v129, v37, v152
	v_mul_f32_e32 v130, v38, v152
	v_mul_f32_e32 v131, v39, v152
	v_mul_f32_e32 v136, v34, v152
	v_mul_f32_e32 v137, v35, v152
	v_max_f32_e32 v128, 0, v128
	v_max_f32_e32 v129, 0, v129
	v_max_f32_e32 v130, 0, v130
	v_max_f32_e32 v131, 0, v131
	v_max_f32_e32 v134, 0, v134
	v_max_f32_e32 v135, 0, v135
	v_max_f32_e32 v136, 0, v136
	v_max_f32_e32 v137, 0, v137
	v_pk_mul_f32 v[128:129], v[128:129], v[128:129]
	v_pk_mul_f32 v[130:131], v[130:131], v[130:131]
	v_pk_mul_f32 v[134:135], v[134:135], v[134:135]
	v_pk_mul_f32 v[136:137], v[136:137], v[136:137]
	v_cvt_pk_bf16_f32 v128, v128, v129
	v_cvt_pk_bf16_f32 v129, v130, v131
	v_cvt_pk_bf16_f32 v130, v134, v135
	v_cvt_pk_bf16_f32 v131, v136, v137
	global_store_dwordx4 v[132:133], v[128:131], off
	v_mul_f32_e32 v134, v0, v152
	v_mul_f32_e32 v135, v1, v152
	v_mul_f32_e32 v128, v4, v152
	v_mul_f32_e32 v129, v5, v152
	v_mul_f32_e32 v130, v6, v152
	v_mul_f32_e32 v131, v7, v152
	v_mul_f32_e32 v136, v2, v152
	v_mul_f32_e32 v137, v3, v152
	v_max_f32_e32 v128, 0, v128
	v_max_f32_e32 v129, 0, v129
	v_max_f32_e32 v130, 0, v130
	v_max_f32_e32 v131, 0, v131
	v_max_f32_e32 v134, 0, v134
	v_max_f32_e32 v135, 0, v135
	v_max_f32_e32 v136, 0, v136
	v_max_f32_e32 v137, 0, v137
	v_pk_mul_f32 v[128:129], v[128:129], v[128:129]
	v_pk_mul_f32 v[130:131], v[130:131], v[130:131]
	v_pk_mul_f32 v[134:135], v[134:135], v[134:135]
	v_pk_mul_f32 v[136:137], v[136:137], v[136:137]
	v_cvt_pk_bf16_f32 v128, v128, v129
	v_cvt_pk_bf16_f32 v129, v130, v131
	v_cvt_pk_bf16_f32 v130, v134, v135
	v_cvt_pk_bf16_f32 v131, v136, v137
	global_store_dwordx4 v[132:133], v[128:131], off offset:256
	s_mov_b64 s[0:1], 0
